# attention: V-fragment LDS reads hoisted above the row-max/rescale decision (on top of SwiGLU/Resid0 epilogue rewrites)
# speedup vs baseline: 1.0142x; 1.0035x over previous
.LBB0_674:
	s_add_i32 s2, s67, -1
	s_and_b32 s2, s2, 3
	s_mulk_i32 s2, 0x3400
	s_and_b32 s71, s67, 2
	s_add_i32 s2, s2, 0
	s_xor_b32 s3, s71, 2
	v_add_u32_e32 v0, s2, v192
	s_mulk_i32 s3, 0x2400
	s_waitcnt vmcnt(5)
	ds_write_b128 v0, v[152:155]
	v_add_u32_e32 v0, s2, v185
	s_add_i32 s2, s67, 5
	s_waitcnt vmcnt(4)
	ds_write_b128 v0, v[156:159] offset:128
	v_add_u32_e32 v0, s3, v193
	s_min_i32 s46, s2, s66
	s_add_i32 s2, s67, 4
	v_add_u32_e32 v0, 0xd000, v0
	s_min_i32 s2, s2, s66
	s_lshl_b64 s[4:5], s[46:47], 16
	s_mov_b32 s3, s47
	s_waitcnt vmcnt(3)
	ds_write2_b64 v0, v[172:173], v[174:175] offset1:2
	v_lshl_add_u64 v[2:3], v[186:187], 0, s[4:5]
	s_lshl_b64 s[4:5], s[46:47], 12
	s_lshl_b64 s[2:3], s[2:3], 7
	v_lshl_add_u64 v[4:5], v[188:189], 0, s[4:5]
	global_load_dwordx4 v[152:155], v[2:3], off
	global_load_dwordx4 v[156:159], v[4:5], off
	v_lshl_add_u64 v[2:3], v[190:191], 0, s[2:3]
	global_load_dwordx4 v[172:175], v[2:3], off
	s_add_i32 s70, s67, 1
	s_and_b32 s69, s70, 3
	s_cmp_gt_i32 s67, s65
	s_cbranch_scc1 .LBB0_685
	s_mul_i32 s2, s69, 0x3400
	v_add_u32_e32 v0, s2, v196
	ds_read_b128 v[2:5], v0
	ds_read_b128 v[6:9], v0 offset:6656
	s_setprio 1
	s_waitcnt lgkmcnt(1)
	v_mfma_f32_32x32x16_bf16 v[112:127], v[2:5], v[128:131], v[48:63]
	ds_read_b128 v[10:13], v0 offset:32
	ds_read_b128 v[202:205], v0 offset:6688
	v_add_f32_e32 v14, 0, v80
	v_add_f32_e32 v14, v81, v14
	v_cvt_pk_bf16_f32 v176, v80, v81
	s_waitcnt lgkmcnt(2)
	v_mfma_f32_32x32x16_bf16 v[96:111], v[6:9], v[128:131], v[48:63]
	v_add_f32_e32 v2, v82, v14
	v_add_f32_e32 v2, v83, v2
	v_add_f32_e32 v14, v84, v2
	v_cvt_pk_bf16_f32 v177, v82, v83
	s_waitcnt lgkmcnt(1)
	v_mfma_f32_32x32x16_bf16 v[112:127], v[10:13], v[132:135], v[112:127]
	ds_read_b128 v[2:5], v0 offset:64
	ds_read_b128 v[6:9], v0 offset:6720
	v_add_f32_e32 v14, v85, v14
	v_add_f32_e32 v14, v86, v14
	v_add_f32_e32 v14, v87, v14
	v_cvt_pk_bf16_f32 v178, v84, v85
	v_cvt_pk_bf16_f32 v179, v86, v87
	s_waitcnt lgkmcnt(2)
	v_mfma_f32_32x32x16_bf16 v[96:111], v[202:205], v[132:135], v[96:111]
	v_add_f32_e32 v10, v88, v14
	v_add_f32_e32 v11, v89, v10
	v_cvt_pk_bf16_f32 v10, v88, v89
	s_waitcnt lgkmcnt(1)
	v_mfma_f32_32x32x16_bf16 v[112:127], v[2:5], v[136:139], v[112:127]
	ds_read_b128 v[80:83], v0 offset:96
	ds_read_b128 v[202:205], v0 offset:6752
	v_add_f32_e32 v11, v90, v11
	v_add_f32_e32 v11, v91, v11
	v_add_f32_e32 v12, v92, v11
	v_cvt_pk_bf16_f32 v11, v90, v91
	s_waitcnt lgkmcnt(2)
	v_mfma_f32_32x32x16_bf16 v[96:111], v[6:9], v[136:139], v[96:111]
	v_add_f32_e32 v2, v93, v12
	v_add_f32_e32 v2, v94, v2
	v_add_f32_e32 v14, v95, v2
	v_cvt_pk_bf16_f32 v12, v92, v93
	v_cvt_pk_bf16_f32 v13, v94, v95
	s_waitcnt lgkmcnt(1)
	v_mfma_f32_32x32x16_bf16 v[112:127], v[80:83], v[140:143], v[112:127]
	ds_read_b128 v[2:5], v0 offset:128
	ds_read_b128 v[206:209], v0 offset:6784
	v_add_f32_e32 v6, v16, v14
	v_add_f32_e32 v7, v17, v6
	v_cvt_pk_bf16_f32 v6, v16, v17
	s_waitcnt lgkmcnt(2)
	v_mfma_f32_32x32x16_bf16 v[96:111], v[202:205], v[140:143], v[96:111]
	v_add_f32_e32 v7, v18, v7
	v_add_f32_e32 v7, v19, v7
	v_add_f32_e32 v8, v20, v7
	v_cvt_pk_bf16_f32 v7, v18, v19
	s_waitcnt lgkmcnt(1)
	v_mfma_f32_32x32x16_bf16 v[112:127], v[2:5], v[144:147], v[112:127]
	ds_read_b128 v[14:17], v0 offset:160
	ds_read_b128 v[80:83], v0 offset:6816
	v_add_f32_e32 v0, v21, v8
	v_add_f32_e32 v0, v22, v0
	v_add_f32_e32 v0, v23, v0
	v_cvt_pk_bf16_f32 v8, v20, v21
	v_cvt_pk_bf16_f32 v9, v22, v23
	s_waitcnt lgkmcnt(2)
	v_mfma_f32_32x32x16_bf16 v[96:111], v[206:209], v[144:147], v[96:111]
	v_add_f32_e32 v0, v24, v0
	v_add_f32_e32 v0, v25, v0
	v_cvt_pk_bf16_f32 v2, v24, v25
	s_waitcnt lgkmcnt(1)
	v_mfma_f32_32x32x16_bf16 v[112:127], v[14:17], v[148:151], v[112:127]
	v_add_f32_e32 v0, v26, v0
	v_add_f32_e32 v0, v27, v0
	v_add_f32_e32 v0, v28, v0
	v_cvt_pk_bf16_f32 v3, v26, v27
	s_waitcnt lgkmcnt(0)
	v_mfma_f32_32x32x16_bf16 v[96:111], v[80:83], v[148:151], v[96:111]
	v_add_f32_e32 v0, v29, v0
	v_add_f32_e32 v0, v30, v0
	v_add_f32_e32 v0, v31, v0
	v_cvt_pk_bf16_f32 v4, v28, v29
	v_cvt_pk_bf16_f32 v5, v30, v31
	s_mul_i32 s4, s71, 0x2400
	v_add_u32_e32 v206, s4, v200
	ds_read_b128 v[16:19], v206 offset:53248
	ds_read_b128 v[202:205], v206 offset:57856
	s_cmp_ge_i32 s67, s65
	s_setprio 0
	v_add_f32_e32 v201, v201, v0
	s_cbranch_scc1 .LBB0_682
	s_sub_i32 s2, s68, 64
	s_cmp_le_i32 s2, s63
	s_cbranch_scc1 .LBB0_680
	v_add_u32_e32 v0, s68, v197
	v_add_u32_e32 v15, 0xffffffa1, v0
	v_add_u32_e32 v14, 0xffffff81, v0
	v_cmp_le_i32_e64 s[2:3], v15, v184
	v_cmp_le_i32_e32 vcc, v14, v184
	s_nop 0
	v_cndmask_b32_e64 v96, v194, v96, s[2:3]
	v_cmp_lt_i32_e64 s[2:3], v14, v184
	v_add_u32_e32 v14, 0xffffffa2, v0
	v_cmp_le_i32_e64 s[4:5], v14, v184
	v_add_u32_e32 v14, 0xffffff83, v0
	s_nop 0
	v_cndmask_b32_e64 v97, v194, v97, s[4:5]
	v_cmp_le_i32_e64 s[4:5], v14, v184
	v_add_u32_e32 v14, 0xffffffa3, v0
	v_cmp_le_i32_e64 s[6:7], v14, v184
	v_add_u32_e32 v14, 0xffffff84, v0
	s_nop 0
	v_cndmask_b32_e64 v98, v194, v98, s[6:7]
	v_cmp_le_i32_e64 s[6:7], v14, v184
	v_add_u32_e32 v14, 0xffffffa4, v0
	v_cmp_le_i32_e64 s[8:9], v14, v184
	v_add_u32_e32 v14, 0xffffff89, v0
	s_nop 0
	v_cndmask_b32_e64 v99, v194, v99, s[8:9]
	v_cmp_le_i32_e64 s[8:9], v14, v184
	v_add_u32_e32 v14, 0xffffffa9, v0
	v_cmp_le_i32_e64 s[10:11], v14, v184
	v_add_u32_e32 v14, 0xffffff8a, v0
	s_nop 0
	v_cndmask_b32_e64 v100, v194, v100, s[10:11]
	v_cmp_le_i32_e64 s[10:11], v14, v184
	v_add_u32_e32 v14, 0xffffffaa, v0
	v_cmp_le_i32_e64 s[12:13], v14, v184
	v_add_u32_e32 v14, 0xffffff8b, v0
	s_nop 0
	v_cndmask_b32_e64 v101, v194, v101, s[12:13]
	v_cmp_le_i32_e64 s[12:13], v14, v184
	v_add_u32_e32 v14, 0xffffffab, v0
	v_cmp_le_i32_e64 s[14:15], v14, v184
	v_add_u32_e32 v14, 0xffffff8c, v0
	s_nop 0
	v_cndmask_b32_e64 v102, v194, v102, s[14:15]
	v_cmp_le_i32_e64 s[14:15], v14, v184
	v_add_u32_e32 v14, 0xffffffac, v0
	v_cmp_le_i32_e64 s[16:17], v14, v184
	v_add_u32_e32 v14, 0xffffff91, v0
	s_nop 0
	v_cndmask_b32_e64 v103, v194, v103, s[16:17]
	v_cmp_le_i32_e64 s[16:17], v14, v184
	v_add_u32_e32 v14, 0xffffffb1, v0
	v_cmp_le_i32_e64 s[18:19], v14, v184
	v_add_u32_e32 v14, 0xffffff92, v0
	s_nop 0
	v_cndmask_b32_e64 v104, v194, v104, s[18:19]
	v_cmp_le_i32_e64 s[18:19], v14, v184
	v_add_u32_e32 v14, 0xffffffb2, v0
	v_cmp_le_i32_e64 s[20:21], v14, v184
	v_add_u32_e32 v14, 0xffffff93, v0
	s_nop 0
	v_cndmask_b32_e64 v105, v194, v105, s[20:21]
	v_cmp_le_i32_e64 s[20:21], v14, v184
	v_add_u32_e32 v14, 0xffffffb3, v0
	v_cmp_le_i32_e64 s[22:23], v14, v184
	v_add_u32_e32 v14, 0xffffff94, v0
	s_nop 0
	v_cndmask_b32_e64 v106, v194, v106, s[22:23]
	v_cmp_le_i32_e64 s[22:23], v14, v184
	v_add_u32_e32 v14, 0xffffffb4, v0
	v_cmp_le_i32_e64 s[24:25], v14, v184
	v_add_u32_e32 v14, 0xffffff99, v0
	s_nop 0
	v_cndmask_b32_e64 v107, v194, v107, s[24:25]
	v_cmp_le_i32_e64 s[24:25], v14, v184
	v_add_u32_e32 v14, 0xffffffb9, v0
	v_cmp_le_i32_e64 s[26:27], v14, v184
	v_add_u32_e32 v14, 0xffffff9a, v0
	s_nop 0
	v_cndmask_b32_e64 v108, v194, v108, s[26:27]
	v_cmp_le_i32_e64 s[26:27], v14, v184
	v_add_u32_e32 v14, 0xffffffba, v0
	v_cmp_le_i32_e64 s[28:29], v14, v184
	v_add_u32_e32 v14, 0xffffff9b, v0
	s_nop 0
	v_cndmask_b32_e64 v109, v194, v109, s[28:29]
	v_cmp_le_i32_e64 s[28:29], v14, v184
	v_add_u32_e32 v14, 0xffffffbb, v0
	v_cmp_le_i32_e64 s[30:31], v14, v184
	v_add_u32_e32 v14, 0xffffff9c, v0
	v_add_u32_e32 v0, 0xffffffbc, v0
	v_cndmask_b32_e64 v110, v194, v110, s[30:31]
	v_cmp_le_i32_e64 s[30:31], v14, v184
	v_cmp_gt_i32_e64 s[34:35], v0, v184
	s_and_saveexec_b64 s[48:49], s[34:35]
	v_mov_b32_e32 v111, s59
	s_or_b64 exec, exec, s[48:49]
	v_cndmask_b32_e64 v113, v194, v113, s[2:3]
	v_cndmask_b32_e32 v112, v194, v112, vcc
	v_cndmask_b32_e64 v114, v194, v114, s[4:5]
	v_cndmask_b32_e64 v115, v194, v115, s[6:7]
	v_cndmask_b32_e64 v116, v194, v116, s[8:9]
	v_cndmask_b32_e64 v117, v194, v117, s[10:11]
	v_cndmask_b32_e64 v118, v194, v118, s[12:13]
	v_cndmask_b32_e64 v119, v194, v119, s[14:15]
	v_cndmask_b32_e64 v120, v194, v120, s[16:17]
	v_cndmask_b32_e64 v121, v194, v121, s[18:19]
	v_cndmask_b32_e64 v122, v194, v122, s[20:21]
	v_cndmask_b32_e64 v123, v194, v123, s[22:23]
	v_cndmask_b32_e64 v124, v194, v124, s[24:25]
	v_cndmask_b32_e64 v125, v194, v125, s[26:27]
	v_cndmask_b32_e64 v126, v194, v126, s[28:29]
	v_cndmask_b32_e64 v127, v194, v127, s[30:31]

.LBB0_683:
	s_setprio 1
	s_waitcnt lgkmcnt(1)
	v_mfma_f32_32x32x16_bf16 v[64:79], v[16:19], v[176:179], v[64:79]
	v_exp_f32_e32 v80, v112
	v_exp_f32_e32 v81, v113
	v_exp_f32_e32 v82, v114
	v_exp_f32_e32 v83, v115
	ds_read_b128 v[112:115], v206 offset:53280
	s_waitcnt lgkmcnt(1)
	v_mfma_f32_32x32x16_bf16 v[32:47], v[202:205], v[176:179], v[32:47]
	ds_read_b128 v[14:17], v206 offset:57888
	v_exp_f32_e32 v84, v116
	v_exp_f32_e32 v85, v117
	v_exp_f32_e32 v86, v118
	v_exp_f32_e32 v87, v119
	s_waitcnt lgkmcnt(1)
	v_mfma_f32_32x32x16_bf16 v[64:79], v[112:115], v[10:13], v[64:79]
	ds_read_b128 v[116:119], v206 offset:53312
	v_exp_f32_e32 v88, v120
	v_exp_f32_e32 v89, v121
	v_exp_f32_e32 v90, v122
	v_exp_f32_e32 v91, v123
	s_waitcnt lgkmcnt(1)
	v_mfma_f32_32x32x16_bf16 v[32:47], v[14:17], v[10:13], v[32:47]
	ds_read_b128 v[112:115], v206 offset:57920
	v_exp_f32_e32 v92, v124
	v_exp_f32_e32 v93, v125
	v_exp_f32_e32 v94, v126
	v_exp_f32_e32 v95, v127
	s_waitcnt lgkmcnt(1)
	v_mfma_f32_32x32x16_bf16 v[64:79], v[116:119], v[6:9], v[64:79]
	ds_read_b128 v[10:13], v206 offset:53344
	v_exp_f32_e32 v16, v96
	v_exp_f32_e32 v17, v97
	v_exp_f32_e32 v18, v98
	v_exp_f32_e32 v19, v99
	s_waitcnt lgkmcnt(1)
	v_mfma_f32_32x32x16_bf16 v[32:47], v[112:115], v[6:9], v[32:47]
	ds_read_b128 v[96:99], v206 offset:57952
	v_exp_f32_e32 v20, v100
	v_exp_f32_e32 v21, v101
	v_exp_f32_e32 v22, v102
	v_exp_f32_e32 v23, v103
	s_waitcnt lgkmcnt(1)
	v_mfma_f32_32x32x16_bf16 v[64:79], v[10:13], v[2:5], v[64:79]
	v_exp_f32_e32 v24, v104
	v_exp_f32_e32 v25, v105
	v_exp_f32_e32 v26, v106
	v_exp_f32_e32 v27, v107
	s_waitcnt lgkmcnt(0)
	v_mfma_f32_32x32x16_bf16 v[32:47], v[96:99], v[2:5], v[32:47]
	v_exp_f32_e32 v28, v108
	v_exp_f32_e32 v29, v109
	v_exp_f32_e32 v30, v110
	v_exp_f32_e32 v31, v111
	s_setprio 0
	s_andn2_b64 vcc, exec, s[2:3]
	s_cbranch_vccnz .LBB0_685
	v_pk_mul_f32 v[78:79], v[0:1], v[78:79] op_sel_hi:[0,1]
	v_pk_mul_f32 v[76:77], v[0:1], v[76:77] op_sel_hi:[0,1]
	v_pk_mul_f32 v[74:75], v[0:1], v[74:75] op_sel_hi:[0,1]
	v_pk_mul_f32 v[72:73], v[0:1], v[72:73] op_sel_hi:[0,1]
	v_pk_mul_f32 v[70:71], v[0:1], v[70:71] op_sel_hi:[0,1]
	v_pk_mul_f32 v[68:69], v[0:1], v[68:69] op_sel_hi:[0,1]
	v_pk_mul_f32 v[66:67], v[0:1], v[66:67] op_sel_hi:[0,1]
	v_pk_mul_f32 v[64:65], v[0:1], v[64:65] op_sel_hi:[0,1]
	v_pk_mul_f32 v[46:47], v[0:1], v[46:47] op_sel_hi:[0,1]
	v_pk_mul_f32 v[44:45], v[0:1], v[44:45] op_sel_hi:[0,1]
	v_pk_mul_f32 v[42:43], v[0:1], v[42:43] op_sel_hi:[0,1]
	v_pk_mul_f32 v[40:41], v[0:1], v[40:41] op_sel_hi:[0,1]
	v_pk_mul_f32 v[38:39], v[0:1], v[38:39] op_sel_hi:[0,1]
	v_pk_mul_f32 v[36:37], v[0:1], v[36:37] op_sel_hi:[0,1]
	v_pk_mul_f32 v[34:35], v[0:1], v[34:35] op_sel_hi:[0,1]
	v_pk_mul_f32 v[32:33], v[0:1], v[32:33] op_sel_hi:[0,1]
.LBB0_685:
	s_mulk_i32 s71, 0x3400
	s_add_i32 s3, s71, 0
	s_xor_b32 s2, s69, 2
	v_add_u32_e32 v0, s3, v192
	s_mulk_i32 s2, 0x2400
	s_waitcnt vmcnt(5)
	ds_write_b128 v0, v[168:171]
	v_add_u32_e32 v0, s3, v185
	s_waitcnt vmcnt(4)
	ds_write_b128 v0, v[164:167] offset:128
	v_add_u32_e32 v0, s2, v193
	s_add_i32 s2, s67, 6
	s_min_i32 s2, s2, s66
	s_mov_b32 s3, s47
	v_add_u32_e32 v0, 0xd000, v0
	s_lshl_b64 s[4:5], s[2:3], 16
	s_lshl_b64 s[2:3], s[2:3], 12
	s_waitcnt vmcnt(3)
	ds_write2_b64 v0, v[160:161], v[162:163] offset1:2
	v_lshl_add_u64 v[2:3], v[186:187], 0, s[4:5]
	v_lshl_add_u64 v[4:5], v[188:189], 0, s[2:3]
	s_lshl_b64 s[2:3], s[46:47], 7
	global_load_dwordx4 v[168:171], v[2:3], off
	global_load_dwordx4 v[164:167], v[4:5], off
	v_lshl_add_u64 v[2:3], v[190:191], 0, s[2:3]
	global_load_dwordx4 v[160:163], v[2:3], off
	s_add_i32 s46, s67, 2
	s_cmp_ge_i32 s67, s65
	s_cbranch_scc1 .LBB0_696
	s_and_b32 s2, s46, 2
	s_mulk_i32 s2, 0x3400
	v_add_u32_e32 v0, s2, v196
	ds_read_b128 v[2:5], v0
	ds_read_b128 v[6:9], v0 offset:6656
	s_setprio 1
	s_waitcnt lgkmcnt(1)
	v_mfma_f32_32x32x16_bf16 v[112:127], v[2:5], v[128:131], v[48:63]
	ds_read_b128 v[10:13], v0 offset:32
	ds_read_b128 v[202:205], v0 offset:6688
	v_add_f32_e32 v14, 0, v80
	v_add_f32_e32 v14, v81, v14
	v_cvt_pk_bf16_f32 v176, v80, v81
	s_waitcnt lgkmcnt(2)
	v_mfma_f32_32x32x16_bf16 v[96:111], v[6:9], v[128:131], v[48:63]
	v_add_f32_e32 v2, v82, v14
	v_add_f32_e32 v2, v83, v2
	v_add_f32_e32 v14, v84, v2
	v_cvt_pk_bf16_f32 v177, v82, v83
	s_waitcnt lgkmcnt(1)
	v_mfma_f32_32x32x16_bf16 v[112:127], v[10:13], v[132:135], v[112:127]
	ds_read_b128 v[2:5], v0 offset:64
	ds_read_b128 v[6:9], v0 offset:6720
	v_add_f32_e32 v14, v85, v14
	v_add_f32_e32 v14, v86, v14
	v_add_f32_e32 v14, v87, v14
	v_cvt_pk_bf16_f32 v178, v84, v85
	v_cvt_pk_bf16_f32 v179, v86, v87
	s_waitcnt lgkmcnt(2)
	v_mfma_f32_32x32x16_bf16 v[96:111], v[202:205], v[132:135], v[96:111]
	v_add_f32_e32 v10, v88, v14
	v_add_f32_e32 v11, v89, v10
	v_cvt_pk_bf16_f32 v10, v88, v89
	s_waitcnt lgkmcnt(1)
	v_mfma_f32_32x32x16_bf16 v[112:127], v[2:5], v[136:139], v[112:127]
	ds_read_b128 v[80:83], v0 offset:96
	ds_read_b128 v[202:205], v0 offset:6752
	v_add_f32_e32 v11, v90, v11
	v_add_f32_e32 v11, v91, v11
	v_add_f32_e32 v12, v92, v11
	v_cvt_pk_bf16_f32 v11, v90, v91
	s_waitcnt lgkmcnt(2)
	v_mfma_f32_32x32x16_bf16 v[96:111], v[6:9], v[136:139], v[96:111]
	v_add_f32_e32 v2, v93, v12
	v_add_f32_e32 v2, v94, v2
	v_add_f32_e32 v14, v95, v2
	v_cvt_pk_bf16_f32 v12, v92, v93
	v_cvt_pk_bf16_f32 v13, v94, v95
	s_waitcnt lgkmcnt(1)
	v_mfma_f32_32x32x16_bf16 v[112:127], v[80:83], v[140:143], v[112:127]
	ds_read_b128 v[2:5], v0 offset:128
	ds_read_b128 v[206:209], v0 offset:6784
	v_add_f32_e32 v6, v16, v14
	v_add_f32_e32 v7, v17, v6
	v_cvt_pk_bf16_f32 v6, v16, v17
	s_waitcnt lgkmcnt(2)
	v_mfma_f32_32x32x16_bf16 v[96:111], v[202:205], v[140:143], v[96:111]
	v_add_f32_e32 v7, v18, v7
	v_add_f32_e32 v7, v19, v7
	v_add_f32_e32 v8, v20, v7
	v_cvt_pk_bf16_f32 v7, v18, v19
	s_waitcnt lgkmcnt(1)
	v_mfma_f32_32x32x16_bf16 v[112:127], v[2:5], v[144:147], v[112:127]
	ds_read_b128 v[14:17], v0 offset:160
	ds_read_b128 v[80:83], v0 offset:6816
	v_add_f32_e32 v0, v21, v8
	v_add_f32_e32 v0, v22, v0
	v_add_f32_e32 v0, v23, v0
	v_cvt_pk_bf16_f32 v8, v20, v21
	v_cvt_pk_bf16_f32 v9, v22, v23
	s_waitcnt lgkmcnt(2)
	v_mfma_f32_32x32x16_bf16 v[96:111], v[206:209], v[144:147], v[96:111]
	v_add_f32_e32 v0, v24, v0
	v_add_f32_e32 v0, v25, v0
	v_cvt_pk_bf16_f32 v2, v24, v25
	s_waitcnt lgkmcnt(1)
	v_mfma_f32_32x32x16_bf16 v[112:127], v[14:17], v[148:151], v[112:127]
	v_add_f32_e32 v0, v26, v0
	v_add_f32_e32 v0, v27, v0
	v_add_f32_e32 v0, v28, v0
	v_cvt_pk_bf16_f32 v3, v26, v27
	s_waitcnt lgkmcnt(0)
	v_mfma_f32_32x32x16_bf16 v[96:111], v[80:83], v[148:151], v[96:111]
	v_add_f32_e32 v0, v29, v0
	v_add_f32_e32 v0, v30, v0
	v_add_f32_e32 v0, v31, v0
	v_cvt_pk_bf16_f32 v4, v28, v29
	v_cvt_pk_bf16_f32 v5, v30, v31
	s_mul_i32 s4, s69, 0x2400
	v_add_u32_e32 v206, s4, v200
	ds_read_b128 v[16:19], v206 offset:53248
	ds_read_b128 v[202:205], v206 offset:57856
	s_cmp_ge_i32 s70, s65
	s_setprio 0
	v_add_f32_e32 v201, v201, v0
	s_cbranch_scc1 .LBB0_693
	s_cmp_le_i32 s68, s63
	s_cbranch_scc1 .LBB0_691
	v_add_u32_e32 v0, s68, v197
	v_subrev_u32_e32 v15, 31, v0
	v_subrev_u32_e32 v14, 63, v0
	v_cmp_le_i32_e64 s[2:3], v15, v184
	v_cmp_le_i32_e32 vcc, v14, v184
	s_nop 0
	v_cndmask_b32_e64 v96, v194, v96, s[2:3]
	v_cmp_lt_i32_e64 s[2:3], v14, v184
	v_subrev_u32_e32 v14, 30, v0
	v_cmp_le_i32_e64 s[4:5], v14, v184
	v_subrev_u32_e32 v14, 61, v0
	s_nop 0
	v_cndmask_b32_e64 v97, v194, v97, s[4:5]
	v_cmp_le_i32_e64 s[4:5], v14, v184
	v_subrev_u32_e32 v14, 29, v0
	v_cmp_le_i32_e64 s[6:7], v14, v184
	v_subrev_u32_e32 v14, 60, v0
	s_nop 0
	v_cndmask_b32_e64 v98, v194, v98, s[6:7]
	v_cmp_le_i32_e64 s[6:7], v14, v184
	v_subrev_u32_e32 v14, 28, v0
	v_cmp_le_i32_e64 s[8:9], v14, v184
	v_subrev_u32_e32 v14, 55, v0
	s_nop 0
	v_cndmask_b32_e64 v99, v194, v99, s[8:9]
	v_cmp_le_i32_e64 s[8:9], v14, v184
	v_subrev_u32_e32 v14, 23, v0
	v_cmp_le_i32_e64 s[10:11], v14, v184
	v_subrev_u32_e32 v14, 54, v0
	s_nop 0
	v_cndmask_b32_e64 v100, v194, v100, s[10:11]
	v_cmp_le_i32_e64 s[10:11], v14, v184
	v_subrev_u32_e32 v14, 22, v0
	v_cmp_le_i32_e64 s[12:13], v14, v184
	v_subrev_u32_e32 v14, 53, v0
	s_nop 0
	v_cndmask_b32_e64 v101, v194, v101, s[12:13]
	v_cmp_le_i32_e64 s[12:13], v14, v184
	v_subrev_u32_e32 v14, 21, v0
	v_cmp_le_i32_e64 s[14:15], v14, v184
	v_subrev_u32_e32 v14, 52, v0
	s_nop 0
	v_cndmask_b32_e64 v102, v194, v102, s[14:15]
	v_cmp_le_i32_e64 s[14:15], v14, v184
	v_subrev_u32_e32 v14, 20, v0
	v_cmp_le_i32_e64 s[16:17], v14, v184
	v_subrev_u32_e32 v14, 47, v0
	s_nop 0
	v_cndmask_b32_e64 v103, v194, v103, s[16:17]
	v_cmp_le_i32_e64 s[16:17], v14, v184
	v_add_u32_e32 v14, -15, v0
	v_cmp_le_i32_e64 s[18:19], v14, v184
	v_subrev_u32_e32 v14, 46, v0
	s_nop 0
	v_cndmask_b32_e64 v104, v194, v104, s[18:19]
	v_cmp_le_i32_e64 s[18:19], v14, v184
	v_add_u32_e32 v14, -14, v0
	v_cmp_le_i32_e64 s[20:21], v14, v184
	v_subrev_u32_e32 v14, 45, v0
	s_nop 0
	v_cndmask_b32_e64 v105, v194, v105, s[20:21]
	v_cmp_le_i32_e64 s[20:21], v14, v184
	v_add_u32_e32 v14, -13, v0
	v_cmp_le_i32_e64 s[22:23], v14, v184
	v_subrev_u32_e32 v14, 44, v0
	s_nop 0
	v_cndmask_b32_e64 v106, v194, v106, s[22:23]
	v_cmp_le_i32_e64 s[22:23], v14, v184
	v_add_u32_e32 v14, -12, v0
	v_cmp_le_i32_e64 s[24:25], v14, v184
	v_subrev_u32_e32 v14, 39, v0
	s_nop 0
	v_cndmask_b32_e64 v107, v194, v107, s[24:25]
	v_cmp_le_i32_e64 s[24:25], v14, v184
	v_add_u32_e32 v14, -7, v0
	v_cmp_le_i32_e64 s[26:27], v14, v184
	v_subrev_u32_e32 v14, 38, v0
	s_nop 0
	v_cndmask_b32_e64 v108, v194, v108, s[26:27]
	v_cmp_le_i32_e64 s[26:27], v14, v184
	v_add_u32_e32 v14, -6, v0
	v_cmp_le_i32_e64 s[28:29], v14, v184
	v_subrev_u32_e32 v14, 37, v0
	s_nop 0
	v_cndmask_b32_e64 v109, v194, v109, s[28:29]
	v_cmp_le_i32_e64 s[28:29], v14, v184
	v_add_u32_e32 v14, -5, v0
	v_cmp_le_i32_e64 s[30:31], v14, v184
	v_subrev_u32_e32 v14, 36, v0
	v_add_u32_e32 v0, -4, v0
	v_cndmask_b32_e64 v110, v194, v110, s[30:31]
	v_cmp_le_i32_e64 s[30:31], v14, v184
	v_cmp_gt_i32_e64 s[34:35], v0, v184
	s_and_saveexec_b64 s[48:49], s[34:35]
	v_mov_b32_e32 v111, s59
	s_or_b64 exec, exec, s[48:49]
	v_cndmask_b32_e64 v113, v194, v113, s[2:3]
	v_cndmask_b32_e32 v112, v194, v112, vcc
	v_cndmask_b32_e64 v114, v194, v114, s[4:5]
	v_cndmask_b32_e64 v115, v194, v115, s[6:7]
	v_cndmask_b32_e64 v116, v194, v116, s[8:9]
	v_cndmask_b32_e64 v117, v194, v117, s[10:11]
	v_cndmask_b32_e64 v118, v194, v118, s[12:13]
	v_cndmask_b32_e64 v119, v194, v119, s[14:15]
	v_cndmask_b32_e64 v120, v194, v120, s[16:17]
	v_cndmask_b32_e64 v121, v194, v121, s[18:19]
	v_cndmask_b32_e64 v122, v194, v122, s[20:21]
	v_cndmask_b32_e64 v123, v194, v123, s[22:23]
	v_cndmask_b32_e64 v124, v194, v124, s[24:25]
	v_cndmask_b32_e64 v125, v194, v125, s[26:27]
	v_cndmask_b32_e64 v126, v194, v126, s[28:29]
	v_cndmask_b32_e64 v127, v194, v127, s[30:31]
